# baseline (speedup 1.0000x reference)
; template <bool WIDE>
; __device__ __forceinline__ void outproj_tile(const Params& P, int l, int mt, int nt, char* smem) {
;     ...
; #pragma unroll 4
;     for (int q = 0; q < 16; ++q) {
;       float4 y = *(const float4*)(cs + r * CSTR + half * 64 + q * 4);
;       float4 xv = *(const float4*)(xin + q * 4);
;       float4 g = *(const float4*)(g1 + q * 4);
;       float4 o = make_float4(xv.x + g.x * y.x, xv.y + g.y * y.y, xv.z + g.z * y.z, xv.w + g.w * y.w);
;       *(float4*)(xo + q * 4) = o;
;     }
.LBB0_728:
	v_lshl_add_u64 v[14:15], v[8:9], 0, s[14:15]
	v_add_co_u32_e32 v28, vcc, 0x11f42000, v14
	v_lshl_add_u64 v[26:27], v[4:5], 0, s[14:15]
	s_nop 0
	v_addc_co_u32_e32 v29, vcc, 0, v15, vcc
	global_load_dwordx4 v[10:13], v[26:27], off
	global_load_dwordx4 v[14:17], v[28:29], off
	global_load_dwordx4 v[96:99], v[26:27], off offset:16
	global_load_dwordx4 v[100:103], v[28:29], off offset:16
	global_load_dwordx4 v[104:107], v[26:27], off offset:32
	global_load_dwordx4 v[108:111], v[28:29], off offset:32
	global_load_dwordx4 v[112:115], v[26:27], off offset:48
	global_load_dwordx4 v[116:119], v[28:29], off offset:48
	ds_read_b128 v[18:21], v2
	ds_read_b128 v[22:25], v2 offset:16
	ds_read_b128 v[120:123], v2 offset:32
	ds_read_b128 v[124:127], v2 offset:48
	v_add_u32_e32 v2, 64, v2
	v_lshl_add_u64 v[30:31], v[6:7], 0, s[14:15]
	s_add_u32 s14, s14, 64
	s_addc_u32 s15, s15, 0
	s_cmpk_lg_i32 s14, 0x100
	s_waitcnt vmcnt(6) lgkmcnt(3)
	v_pk_fma_f32 v[10:11], v[18:19], v[14:15], v[10:11]
	v_pk_fma_f32 v[12:13], v[20:21], v[16:17], v[12:13]
	global_store_dwordx4 v[30:31], v[10:13], off
	s_waitcnt vmcnt(5) lgkmcnt(2)
	v_pk_fma_f32 v[96:97], v[22:23], v[100:101], v[96:97]
	v_pk_fma_f32 v[98:99], v[24:25], v[102:103], v[98:99]
	global_store_dwordx4 v[30:31], v[96:99], off offset:16
	s_waitcnt vmcnt(4) lgkmcnt(1)
	v_pk_fma_f32 v[104:105], v[120:121], v[108:109], v[104:105]
	v_pk_fma_f32 v[106:107], v[122:123], v[110:111], v[106:107]
	global_store_dwordx4 v[30:31], v[104:107], off offset:32
	s_waitcnt vmcnt(3) lgkmcnt(0)
	v_pk_fma_f32 v[112:113], v[124:125], v[116:117], v[112:113]
	v_pk_fma_f32 v[114:115], v[126:127], v[118:119], v[114:115]
	global_store_dwordx4 v[30:31], v[112:115], off offset:48
	s_cbranch_scc1 .LBB0_728
	s_add_i32 s35, s35, s94
	s_add_i32 s34, s34, s94
	s_cmpk_lt_i32 s35, 0x80
	s_barrier
	s_cbranch_scc1 .LBB0_721
